# add static round-robin assignment of m1 queue items (no atomic dequeue)
# baseline (speedup 1.0000x reference)
.LBB0_860:
	s_mov_b32 s4, s3
	s_mov_b32 s5, -1
	s_cmp_lt_u32 s94, 0x10000
	v_mbcnt_lo_u32_b32 v0, s5, 0
	v_mbcnt_hi_u32_b32 v0, s5, v0
	v_lshl_add_u32 v188, s4, 6, v0
	s_cselect_b64 s[4:5], -1, 0
	s_and_b64 s[4:5], s[28:29], s[4:5]
	s_andn2_b64 vcc, exec, s[4:5]
	s_mov_b64 s[4:5], -1
	s_cbranch_vccnz .LBB0_863
	s_and_b64 vcc, exec, s[4:5]
	s_cbranch_vccnz .LBB0_868

.LBB0_868:
	s_cmp_lt_u32 s94, 2
	s_cbranch_scc0 .Lstat_q
	s_lshl_b32 s4, s94, 5
	v_readlane_b32 s5, v255, 3
	s_add_i32 s63, s5, s4
	s_branch .Lstat_j
.Lstat_q:
	s_lshl_b32 s4, s94, 8
	s_add_i32 s63, s2, s4
.Lstat_j:
	s_barrier
	s_cmp_ge_i32 s63, s96
	s_mov_b32 s8, 2
	s_cbranch_scc1 .LBB0_965
